# v011 + attention fast tiles commit next K/V tile to LDS mid P.V instead of at tile end
# speedup vs baseline: 1.0118x; 1.0042x over previous
; #define LAS __attribute__((address_space(3)))
; #define MFMA16(a, b, c) __builtin_amdgcn_mfma_f32_16x16x32_bf16((a), (b), (c), 0, 0, 0)
; DI u32x2 tr4(const LAS unsigned char* p) { return __builtin_bit_cast(u32x2, __builtin_amdgcn_ds_read_tr16_b64_v4i16((LAS v4i16_t*)p)); }
; DI bf16x8 packp(f32x4 a, f32x4 b) { return __builtin_bit_cast(bf16x8, pack8(a, b)); }
; DI void atb_commit(const AtRawB& r, LAS unsigned char* buf, int tid) {
; #pragma unroll
;     for (int c = 0; c < 2; ++c) { const int e = tid + c * NTHR, key = e >> 4, c8 = (e & 15) * 8;
;         *(LAS u32x4*)(buf + AT_K + key * 272 + c8 * 2) = r.k[c]; *(LAS u32x4*)(buf + AT_V + key * 288 + c8 * 2) = r.v[c]; }
; }
; DI void at_pv(AtState& S, const f32x4 (&s1)[4], const f32x4 (&s2)[4], float alpha, float ps1, float ps2, const LAS unsigned char* buf, int hh, int fq, int tq, int tp) {
;     S.l1 = S.l1 * alpha + ps1; S.l2 = S.l2 * alpha + ps2;
; #pragma unroll
;     for (int dt = 0; dt < 4; ++dt) { S.O1[dt] = S.O1[dt] * alpha; S.O2[dt] = S.O2[dt] * alpha; }
;     bf16x8 p1[2], p2[2];
; #pragma unroll
;     for (int s = 0; s < 2; ++s) { p1[s] = packp(s1[2 * s], s1[2 * s + 1]); p2[s] = packp(s2[2 * s], s2[2 * s + 1]); }
; #pragma unroll
;     for (int dh = 0; dh < 2; ++dh) {
;         bf16x8 vt[2][2];
; #pragma unroll
;         for (int d2 = 0; d2 < 2; ++d2)
; #pragma unroll
;             for (int s = 0; s < 2; ++s) { const int dt = 2 * dh + d2; const LAS unsigned char* vr = buf + AT_V + (32 * s + 4 * fq + tq) * 288 + (hh * 64 + 16 * dt + 4 * tp) * 2; vt[d2][s] = cat44(tr4(vr), tr4(vr + 16 * 288)); }
;         __builtin_amdgcn_s_setprio(1);
; #pragma unroll
;         for (int s = 0; s < 2; ++s)
; #pragma unroll
;             for (int d2 = 0; d2 < 2; ++d2) { const int dt = 2 * dh + d2; S.O1[dt] = MFMA16(vt[d2][s], p1[s], S.O1[dt]); S.O2[dt] = MFMA16(vt[d2][s], p2[s], S.O2[dt]); }
;         __builtin_amdgcn_s_setprio(0);
;         __builtin_amdgcn_sched_barrier(0);
;     }
.LBB0_1379:
	v_cvt_pk_bf16_f32 v216, v164, v165
	v_cvt_pk_bf16_f32 v219, v176, v177
	v_cvt_pk_bf16_f32 v165, v174, v175
	ds_read_b64_tr_b16 v[108:109], v208 offset:17408
	ds_read_b64_tr_b16 v[112:113], v208 offset:17440
	ds_read_b64_tr_b16 v[110:111], v208 offset:22016
	ds_read_b64_tr_b16 v[116:117], v208 offset:26624
	ds_read_b64_tr_b16 v[118:119], v208 offset:31232
	ds_read_b64_tr_b16 v[114:115], v208 offset:22048
	ds_read_b64_tr_b16 v[174:175], v208 offset:26656
	ds_read_b64_tr_b16 v[176:177], v208 offset:31264
	v_mov_b32_e32 v151, v150
	v_pk_fma_f32 v[158:159], v[154:155], v[156:157], v[194:195]
	v_pk_mul_f32 v[78:79], v[150:151], v[66:67]
	v_pk_mul_f32 v[76:77], v[152:153], v[64:65]
	v_pk_mul_f32 v[82:83], v[150:151], v[74:75]
	v_pk_mul_f32 v[80:81], v[152:153], v[72:73]
	v_pk_mul_f32 v[98:99], v[150:151], v[62:63]
	v_pk_mul_f32 v[96:97], v[152:153], v[60:61]
	v_pk_mul_f32 v[106:107], v[150:151], v[70:71]
	v_pk_mul_f32 v[104:105], v[152:153], v[68:69]
	v_pk_mul_f32 v[126:127], v[150:151], v[90:91]
	v_pk_mul_f32 v[124:125], v[152:153], v[88:89]
	v_pk_mul_f32 v[130:131], v[150:151], v[102:103]
	v_pk_mul_f32 v[128:129], v[152:153], v[100:101]
	v_pk_mul_f32 v[134:135], v[150:151], v[86:87]
	v_pk_mul_f32 v[132:133], v[152:153], v[84:85]
	v_pk_mul_f32 v[138:139], v[150:151], v[94:95]
	v_pk_mul_f32 v[136:137], v[152:153], v[92:93]
	v_cvt_pk_bf16_f32 v217, v168, v169
	v_cvt_pk_bf16_f32 v218, v172, v173
	v_cvt_pk_bf16_f32 v162, v162, v163
	v_cvt_pk_bf16_f32 v163, v166, v167
	v_cvt_pk_bf16_f32 v164, v170, v171
	v_cvt_pk_bf16_f32 v166, v180, v181
	v_cvt_pk_bf16_f32 v167, v184, v185
	v_cvt_pk_bf16_f32 v168, v188, v189
	v_cvt_pk_bf16_f32 v169, v192, v193
	v_cvt_pk_bf16_f32 v170, v178, v179
	v_cvt_pk_bf16_f32 v171, v182, v183
	v_cvt_pk_bf16_f32 v172, v186, v187
	v_cvt_pk_bf16_f32 v173, v190, v191
	s_setprio 1
	s_waitcnt lgkmcnt(5)
	v_mfma_f32_16x16x32_bf16 v[76:79], v[108:111], v[216:219], v[76:79]
	v_mfma_f32_16x16x32_bf16 v[80:83], v[108:111], v[162:165], v[80:83]
	s_waitcnt lgkmcnt(2)
	v_mfma_f32_16x16x32_bf16 v[96:99], v[112:115], v[216:219], v[96:99]
	v_mfma_f32_16x16x32_bf16 v[104:107], v[112:115], v[162:165], v[104:107]
	v_mfma_f32_16x16x32_bf16 v[120:123], v[116:119], v[166:169], v[76:79]
	v_mfma_f32_16x16x32_bf16 v[116:119], v[116:119], v[170:173], v[80:83]
	s_waitcnt lgkmcnt(0)
	v_mfma_f32_16x16x32_bf16 v[112:115], v[174:177], v[166:169], v[96:99]
	v_mfma_f32_16x16x32_bf16 v[108:111], v[174:177], v[170:173], v[104:107]
	s_setprio 0
	s_waitcnt vmcnt(4)
	ds_write_b128 v143, v[12:15] offset:35840
	ds_write_b128 v202, v[16:19] offset:53248
	ds_write_b128 v203, v[20:23] offset:35840
	ds_write_b128 v204, v[24:27] offset:53248
	ds_read_b64_tr_b16 v[76:77], v208 offset:17472
	ds_read_b64_tr_b16 v[80:81], v208 offset:17504
	ds_read_b64_tr_b16 v[78:79], v208 offset:22080
	ds_read_b64_tr_b16 v[82:83], v208 offset:22112
	ds_read_b64_tr_b16 v[96:97], v208 offset:26688
	ds_read_b64_tr_b16 v[98:99], v208 offset:31296
	ds_read_b64_tr_b16 v[106:107], v208 offset:31328
	ds_read_b64_tr_b16 v[104:105], v208 offset:26720
	s_setprio 1
	s_waitcnt lgkmcnt(5)
	v_mfma_f32_16x16x32_bf16 v[124:127], v[76:79], v[216:219], v[124:127]
	v_mfma_f32_16x16x32_bf16 v[76:79], v[76:79], v[162:165], v[128:131]
	s_waitcnt lgkmcnt(4)
	v_mfma_f32_16x16x32_bf16 v[128:131], v[80:83], v[216:219], v[132:135]
	v_mfma_f32_16x16x32_bf16 v[80:83], v[80:83], v[162:165], v[136:139]
	s_waitcnt lgkmcnt(2)
	v_mfma_f32_16x16x32_bf16 v[136:139], v[96:99], v[166:169], v[124:127]
	v_mfma_f32_16x16x32_bf16 v[132:135], v[96:99], v[170:173], v[76:79]
	s_waitcnt lgkmcnt(0)
	v_mfma_f32_16x16x32_bf16 v[128:131], v[104:107], v[166:169], v[128:131]
	v_mfma_f32_16x16x32_bf16 v[124:127], v[104:107], v[170:173], v[80:83]
	s_setprio 0
	s_nop 1
	v_mov_b64_e32 v[82:83], v[58:59]
	v_mov_b64_e32 v[78:79], v[46:47]
	v_mov_b64_e32 v[98:99], v[50:51]
	v_mov_b64_e32 v[106:107], v[54:55]
	v_mov_b32_e32 v3, v215
	v_mov_b64_e32 v[80:81], v[56:57]
	v_mov_b64_e32 v[76:77], v[44:45]
	v_mov_b64_e32 v[96:97], v[48:49]
	v_mov_b64_e32 v[104:105], v[52:53]
	s_mov_b64 s[18:19], 0
	s_branch .Lcommit_done_A

; DI void lds_barrier() { asm volatile("s_waitcnt lgkmcnt(0)" ::: "memory"); __builtin_amdgcn_s_barrier(); asm volatile("" ::: "memory"); }
; template <int VAR>
; DI void attn_tile(AtState& S, const LAS unsigned char* buf, const bf16x8 q1, const bf16x8 q2, int kt, bool diag, int qpos0, int qpos_l, float slope2, float adv, float decay, int hh, int fr, int fq) {
;     ...
;         asm volatile("; attention: fast tile" ::: "memory");
;         at_qk(s1, s2, buf, q1, q2, S.cinit, hh, fr, fq);
;         S.ref += adv;
;         at_exp(s1, s2, ps1, ps2);
;         if (__any(!(ps1 + ps2 < 0x1p60f))) {
;             asm volatile("; attention: bump" ::: "memory");
;             at_qk(s1, s2, buf, q1, q2, S.cinit, hh, fr, fq);
;             float lm = -1e30f;
; #pragma unroll
;             for (int k4 = 0; k4 < 4; ++k4)
; #pragma unroll
;                 for (int j = 0; j < 4; ++j) lm = fmaxf(lm, fmaxf(s1[k4][j], s2[k4][j]));
;             lm = fmaxf(lm, __shfl_xor(lm, 16)); lm = fmaxf(lm, __shfl_xor(lm, 32));
; template <int VAR>
; DI void attn_segment(const Args& a, const Frame& F, int l, int qrow0, int qpos0, int hp, int ntile, int nf32, const float* ck, const float* cv, int prow0) {
;     ...
;         for (int kt = 0; kt < ntile; kt += 2) {
;             atb_issue(rb, pb + (size_t)(kt + 2 < nl ? kt + 2 : nl) * TSTR, voff);
;             attn_tile<VAR>(S, F.lds + (kt & 1) * AT_BUF, q1, q2, kt, kt + 1 == ntile, qpos0, qpos_l, slope2, adv, decay, hh, fr, fq);
;             atb_commit(ra, F.lds + ((kt + 1) & 1) * AT_BUF, tid);
;             lds_barrier();
;             if (kt + 1 >= ntile) break;
;             atb_issue(ra, pb + (size_t)(kt + 3 < nl ? kt + 3 : nl) * TSTR, voff);
;             attn_tile<VAR>(S, F.lds + ((kt + 1) & 1) * AT_BUF, q1, q2, kt + 1, kt + 2 == ntile, qpos0, qpos_l, slope2, adv, decay, hh, fr, fq);
.Lcommit_done_A:
	s_waitcnt lgkmcnt(0)
	s_barrier
	s_add_i32 s14, s26, -2
	s_cmp_ge_i32 s14, s24
	s_mov_b64 s[14:15], -1
	s_cbranch_scc1 .LBB0_1375
	s_min_i32 s14, s26, s25
	s_ashr_i32 s15, s14, 31
	s_lshl_b64 s[14:15], s[14:15], 18
	s_add_u32 s14, s0, s14
	s_addc_u32 s15, s1, s15
	v_lshl_add_u64 v[16:17], s[14:15], 0, v[144:145]
	v_lshl_add_u64 v[24:25], s[14:15], 0, v[146:147]
	global_load_dwordx4 v[12:15], v[16:17], off offset:1024
	s_nop 0
	global_load_dwordx4 v[16:19], v[16:17], off offset:1536
	s_nop 0
	global_load_dwordx4 v[20:23], v[24:25], off offset:1024
	s_nop 0
	global_load_dwordx4 v[24:27], v[24:25], off offset:1536
	s_cmpk_lg_i32 s28, 0x41
	s_mov_b64 s[14:15], -1
	s_cbranch_scc0 .LBB0_1391
	ds_read_b128 v[44:47], v213 offset:35840
	ds_read_b128 v[48:51], v213 offset:35904
	ds_read_b128 v[52:55], v213 offset:40192
	ds_read_b128 v[56:59], v213 offset:40256
	ds_read_b128 v[60:63], v213 offset:44544
	ds_read_b128 v[64:67], v213 offset:44608
	ds_read_b128 v[68:71], v213 offset:48896
	ds_read_b128 v[72:75], v213 offset:48960
	s_waitcnt lgkmcnt(7)
	v_mfma_f32_16x16x32_bf16 v[44:47], v[44:47], v[4:7], v[76:79]
	v_add_f32_e32 v215, v205, v3
	s_waitcnt lgkmcnt(6)
	v_mfma_f32_16x16x32_bf16 v[48:51], v[48:51], v[8:11], v[76:79]
	s_waitcnt lgkmcnt(5)
	v_mfma_f32_16x16x32_bf16 v[52:55], v[52:55], v[4:7], v[96:99]
	s_nop 2
	v_exp_f32_e32 v164, v44
	v_exp_f32_e32 v165, v45
	v_exp_f32_e32 v168, v46
	s_waitcnt lgkmcnt(4)
	v_mfma_f32_16x16x32_bf16 v[56:59], v[56:59], v[8:11], v[96:99]
	v_exp_f32_e32 v169, v47
	v_exp_f32_e32 v162, v48
	v_exp_f32_e32 v163, v49
	s_waitcnt lgkmcnt(3)
	v_mfma_f32_16x16x32_bf16 v[60:63], v[60:63], v[4:7], v[104:107]
	v_exp_f32_e32 v166, v50
	v_exp_f32_e32 v167, v51
	v_exp_f32_e32 v172, v52
	s_waitcnt lgkmcnt(2)
	v_mfma_f32_16x16x32_bf16 v[44:47], v[64:67], v[8:11], v[104:107]
	v_exp_f32_e32 v170, v56
	v_exp_f32_e32 v173, v53
	v_exp_f32_e32 v176, v54
	s_waitcnt lgkmcnt(1)
	v_mfma_f32_16x16x32_bf16 v[48:51], v[68:71], v[4:7], v[80:83]
	v_exp_f32_e32 v177, v55
	v_exp_f32_e32 v174, v58
	v_exp_f32_e32 v175, v59
	s_waitcnt lgkmcnt(0)
	v_mfma_f32_16x16x32_bf16 v[64:67], v[72:75], v[8:11], v[80:83]
	v_exp_f32_e32 v171, v57
	v_exp_f32_e32 v180, v60
	v_exp_f32_e32 v178, v44
	v_exp_f32_e32 v181, v61
	v_exp_f32_e32 v179, v45
	v_exp_f32_e32 v184, v62
	v_exp_f32_e32 v185, v63
	v_exp_f32_e32 v182, v46
	v_exp_f32_e32 v183, v47
	v_exp_f32_e32 v188, v48
	v_exp_f32_e32 v186, v64
	v_exp_f32_e32 v189, v49
	v_exp_f32_e32 v192, v50
	v_exp_f32_e32 v193, v51
	v_exp_f32_e32 v190, v66
	v_exp_f32_e32 v191, v67
	v_exp_f32_e32 v187, v65
	v_pk_add_f32 v[84:85], v[164:165], 0 op_sel_hi:[1,0]
	v_pk_add_f32 v[86:87], v[168:169], 0 op_sel_hi:[1,0]
	v_pk_add_f32 v[68:69], v[162:163], 0 op_sel_hi:[1,0]
	v_pk_add_f32 v[70:71], v[166:167], 0 op_sel_hi:[1,0]
	v_pk_add_f32 v[52:53], v[86:87], v[176:177]
	v_pk_add_f32 v[54:55], v[84:85], v[172:173]
	v_pk_add_f32 v[56:57], v[70:71], v[174:175]
	v_pk_add_f32 v[58:59], v[68:69], v[170:171]
	v_pk_add_f32 v[44:45], v[54:55], v[180:181]
	v_pk_add_f32 v[46:47], v[52:53], v[184:185]
	v_pk_add_f32 v[52:53], v[58:59], v[178:179]
	v_pk_add_f32 v[54:55], v[56:57], v[182:183]
	v_pk_add_f32 v[46:47], v[46:47], v[192:193]
	v_pk_add_f32 v[44:45], v[44:45], v[188:189]
	v_pk_add_f32 v[48:49], v[54:55], v[190:191]
	v_pk_add_f32 v[50:51], v[52:53], v[186:187]
	v_mov_b32_e32 v53, v44
	v_mov_b32_e32 v52, v50
	v_mov_b32_e32 v44, v51
	v_mov_b32_e32 v50, v48
	v_mov_b32_e32 v51, v46
	v_mov_b32_e32 v46, v49
	v_pk_add_f32 v[44:45], v[52:53], v[44:45]
	v_pk_add_f32 v[46:47], v[50:51], v[46:47]
	s_nop 0
	v_pk_add_f32 v[194:195], v[44:45], v[46:47]
	s_nop 0
	v_add_f32_e32 v44, v195, v194
	v_cmp_ngt_f32_e32 vcc, s65, v44
	s_cbranch_vccz .LBB0_1395
	ds_read_b128 v[44:47], v213 offset:35840
	ds_read_b128 v[48:51], v213 offset:35904
	ds_read_b128 v[52:55], v213 offset:40192
	ds_read_b128 v[56:59], v213 offset:40256
	ds_read_b128 v[60:63], v213 offset:44544
	ds_read_b128 v[64:67], v213 offset:44608
	ds_read_b128 v[68:71], v213 offset:48896
	ds_read_b128 v[72:75], v213 offset:48960
	s_waitcnt lgkmcnt(7)
	v_mfma_f32_16x16x32_bf16 v[44:47], v[44:47], v[4:7], v[76:79]
	s_waitcnt lgkmcnt(6)
	v_mfma_f32_16x16x32_bf16 v[48:51], v[48:51], v[8:11], v[76:79]
	s_nop 5
	v_max_f32_e32 v85, v44, v44
	v_max_f32_e32 v86, v45, v45
	v_max_f32_e32 v87, v47, v47
	s_waitcnt lgkmcnt(5)
	v_mfma_f32_16x16x32_bf16 v[52:55], v[52:55], v[4:7], v[96:99]
	s_waitcnt lgkmcnt(4)
	v_mfma_f32_16x16x32_bf16 v[56:59], v[56:59], v[8:11], v[96:99]
	v_max_f32_e32 v84, v48, v48
	v_max_f32_e32 v84, v85, v84
	v_max_f32_e32 v85, v49, v49
	v_max_f32_e32 v85, v86, v85
	v_max3_f32 v84, v84, s60, v85
	v_max_f32_e32 v85, v50, v50
	v_max_f32_e32 v86, v46, v46
	v_max_f32_e32 v85, v86, v85
	v_max_f32_e32 v86, v51, v51
	v_max_f32_e32 v86, v87, v86
	v_max3_f32 v84, v84, v85, v86
	v_max_f32_e32 v85, v56, v56
	v_max_f32_e32 v86, v52, v52
	v_max_f32_e32 v85, v86, v85
	v_max_f32_e32 v86, v57, v57
	v_max_f32_e32 v87, v53, v53
	s_waitcnt lgkmcnt(3)
	v_mfma_f32_16x16x32_bf16 v[60:63], v[60:63], v[4:7], v[104:107]
	v_max_f32_e32 v86, v87, v86
	v_max3_f32 v84, v84, v85, v86
	v_max_f32_e32 v85, v58, v58
	s_waitcnt lgkmcnt(2)
	v_mfma_f32_16x16x32_bf16 v[64:67], v[64:67], v[8:11], v[104:107]
	v_max_f32_e32 v86, v54, v54
	v_max_f32_e32 v85, v86, v85
	v_max_f32_e32 v86, v59, v59
	v_max_f32_e32 v87, v55, v55
	v_max_f32_e32 v86, v87, v86
	v_max3_f32 v84, v84, v85, v86
	s_nop 1
	v_max_f32_e32 v85, v64, v64
	v_max_f32_e32 v86, v60, v60
	v_max_f32_e32 v85, v86, v85
	v_max_f32_e32 v86, v65, v65
	v_max_f32_e32 v87, v61, v61
	s_waitcnt lgkmcnt(1)
; #define LAS __attribute__((address_space(3)))
; DI float fast_exp2(float x) { return __builtin_amdgcn_exp2f(x); }
; DI u32x2 tr4(const LAS unsigned char* p) { return __builtin_bit_cast(u32x2, __builtin_amdgcn_ds_read_tr16_b64_v4i16((LAS v4i16_t*)p)); }
; DI bf16x8 packp(f32x4 a, f32x4 b) { return __builtin_bit_cast(bf16x8, pack8(a, b)); }
; DI void at_pv(AtState& S, const f32x4 (&s1)[4], const f32x4 (&s2)[4], float alpha, float ps1, float ps2, const LAS unsigned char* buf, int hh, int fq, int tq, int tp) {
;     S.l1 = S.l1 * alpha + ps1; S.l2 = S.l2 * alpha + ps2;
; #pragma unroll
;     for (int dt = 0; dt < 4; ++dt) { S.O1[dt] = S.O1[dt] * alpha; S.O2[dt] = S.O2[dt] * alpha; }
;     bf16x8 p1[2], p2[2];
; #pragma unroll
;     for (int s = 0; s < 2; ++s) { p1[s] = packp(s1[2 * s], s1[2 * s + 1]); p2[s] = packp(s2[2 * s], s2[2 * s + 1]); }
; #pragma unroll
;     for (int dh = 0; dh < 2; ++dh) {
;         bf16x8 vt[2][2];
; #pragma unroll
;         for (int d2 = 0; d2 < 2; ++d2)
; #pragma unroll
;             for (int s = 0; s < 2; ++s) { const int dt = 2 * dh + d2; const LAS unsigned char* vr = buf + AT_V + (32 * s + 4 * fq + tq) * 288 + (hh * 64 + 16 * dt + 4 * tp) * 2; vt[d2][s] = cat44(tr4(vr), tr4(vr + 16 * 288)); }
; template <int VAR>
; DI void attn_tile(AtState& S, const LAS unsigned char* buf, const bf16x8 q1, const bf16x8 q2, int kt, bool diag, int qpos0, int qpos_l, float slope2, float adv, float decay, int hh, int fr, int fq) {
;     ...
;             float lm = -1e30f;
; #pragma unroll
;             for (int k4 = 0; k4 < 4; ++k4)
; #pragma unroll
;                 for (int j = 0; j < 4; ++j) lm = fmaxf(lm, fmaxf(s1[k4][j], s2[k4][j]));
;             lm = fmaxf(lm, __shfl_xor(lm, 16)); lm = fmaxf(lm, __shfl_xor(lm, 32));
;             const float bump = fmaxf(lm, 0.f);
;             const float alpha = decay * fast_exp2(-bump); S.ref += bump;
; #pragma unroll
;             for (int k4 = 0; k4 < 4; ++k4) { s1[k4] = s1[k4] - bump; s2[k4] = s2[k4] - bump; S.cinit[k4] = S.cinit[k4] - bump; }
;             at_exp(s1, s2, ps1, ps2);
;             at_pv(S, s1, s2, alpha, ps1, ps2, buf, hh, fq, tq, tp);
	v_mfma_f32_16x16x32_bf16 v[68:71], v[68:71], v[4:7], v[80:83]
	v_max_f32_e32 v86, v87, v86
	v_max3_f32 v84, v84, v85, v86
	v_max_f32_e32 v85, v66, v66
	s_waitcnt lgkmcnt(0)
	v_mfma_f32_16x16x32_bf16 v[72:75], v[72:75], v[8:11], v[80:83]
	v_max_f32_e32 v86, v62, v62
	v_max_f32_e32 v85, v86, v85
	v_max_f32_e32 v86, v67, v67
	v_max_f32_e32 v87, v63, v63
	v_max_f32_e32 v86, v87, v86
	v_max3_f32 v84, v84, v85, v86
	s_nop 1
	v_max_f32_e32 v85, v72, v72
	v_max_f32_e32 v86, v68, v68
	v_max_f32_e32 v85, v86, v85
	v_max_f32_e32 v86, v73, v73
	v_max_f32_e32 v87, v69, v69
	v_max_f32_e32 v86, v87, v86
	v_max3_f32 v84, v84, v85, v86
	v_max_f32_e32 v85, v74, v74
	v_max_f32_e32 v86, v70, v70
	v_max_f32_e32 v85, v86, v85
	v_max_f32_e32 v86, v75, v75
	v_max_f32_e32 v87, v71, v71
	v_max_f32_e32 v86, v87, v86
	v_max3_f32 v84, v84, v85, v86
	v_and_b32_e32 v86, 64, v198
	v_xor_b32_e32 v85, 16, v198
	v_add_u32_e32 v86, 64, v86
	v_cmp_lt_i32_e32 vcc, v85, v86
	s_nop 1
	v_cndmask_b32_e32 v85, v198, v85, vcc
	v_lshlrev_b32_e32 v85, 2, v85
	ds_bpermute_b32 v85, v85, v84
	s_waitcnt lgkmcnt(0)
	v_max_f32_e32 v85, v85, v85
	v_max_f32_e32 v84, v84, v85
	v_xor_b32_e32 v85, 32, v198
	v_cmp_lt_i32_e32 vcc, v85, v86
	s_nop 1
	v_cndmask_b32_e32 v85, v198, v85, vcc
	v_lshlrev_b32_e32 v85, 2, v85
	ds_bpermute_b32 v85, v85, v84
	s_waitcnt lgkmcnt(0)
	v_max3_f32 v84, v84, v85, 0
	v_sub_f32_e32 v86, v47, v84
	v_sub_f32_e32 v87, v46, v84
	v_sub_f32_e32 v88, v45, v84
	v_sub_f32_e32 v89, v44, v84
	v_sub_f32_e32 v90, v51, v84
	v_sub_f32_e32 v91, v50, v84
	v_sub_f32_e32 v92, v49, v84
	v_sub_f32_e32 v93, v48, v84
	v_sub_f32_e32 v94, v55, v84
	v_sub_f32_e32 v95, v54, v84
	v_sub_f32_e32 v101, v53, v84
	v_sub_f32_e32 v102, v52, v84
	v_sub_f32_e32 v103, v59, v84
	v_sub_f32_e32 v151, v58, v84
	v_sub_f32_e32 v156, v57, v84
	v_sub_f32_e32 v157, v56, v84
	v_exp_f32_e32 v216, v89
	v_exp_f32_e32 v220, v93
	v_exp_f32_e32 v217, v88
	v_exp_f32_e32 v221, v92
	v_exp_f32_e32 v218, v87
	v_exp_f32_e32 v222, v91
	v_exp_f32_e32 v219, v86
	v_exp_f32_e32 v223, v90
	v_sub_f32_e32 v237, v63, v84
	v_sub_f32_e32 v236, v62, v84
	v_sub_f32_e32 v233, v61, v84
	v_sub_f32_e32 v232, v60, v84
	v_sub_f32_e32 v239, v67, v84
	v_sub_f32_e32 v238, v66, v84
	v_sub_f32_e32 v235, v65, v84
	v_sub_f32_e32 v234, v64, v84
	v_exp_f32_e32 v224, v102
	v_exp_f32_e32 v226, v157
	v_exp_f32_e32 v225, v101
	v_exp_f32_e32 v227, v156
	v_exp_f32_e32 v228, v95
	v_exp_f32_e32 v230, v151
	v_exp_f32_e32 v229, v94
	v_exp_f32_e32 v231, v103
	v_sub_f32_e32 v71, v71, v84
	v_sub_f32_e32 v70, v70, v84
	v_sub_f32_e32 v69, v69, v84
	v_sub_f32_e32 v68, v68, v84
	v_sub_f32_e32 v75, v75, v84
	v_sub_f32_e32 v74, v74, v84
	v_sub_f32_e32 v73, v73, v84
	v_sub_f32_e32 v72, v72, v84
	v_exp_f32_e32 v232, v232
	v_exp_f32_e32 v234, v234
	v_exp_f32_e32 v233, v233
	v_exp_f32_e32 v235, v235
	v_exp_f32_e32 v236, v236
	v_exp_f32_e32 v238, v238
	v_exp_f32_e32 v237, v237
	v_exp_f32_e32 v239, v239
	v_exp_f32_e32 v240, v68
	v_exp_f32_e32 v242, v72
	v_exp_f32_e32 v241, v69
	v_exp_f32_e32 v243, v73
	v_exp_f32_e32 v244, v70
	v_exp_f32_e32 v246, v74
	v_exp_f32_e32 v245, v71
	v_exp_f32_e32 v247, v75
	v_pk_add_f32 v[60:61], v[216:217], 0 op_sel_hi:[1,0]
	v_pk_add_f32 v[62:63], v[218:219], 0 op_sel_hi:[1,0]
	v_pk_add_f32 v[64:65], v[220:221], 0 op_sel_hi:[1,0]
	v_pk_add_f32 v[66:67], v[222:223], 0 op_sel_hi:[1,0]
	v_pk_add_f32 v[62:63], v[228:229], v[62:63]
	v_pk_add_f32 v[60:61], v[224:225], v[60:61]
	v_pk_add_f32 v[66:67], v[230:231], v[66:67]
	v_pk_add_f32 v[64:65], v[226:227], v[64:65]
	v_pk_add_f32 v[60:61], v[232:233], v[60:61]
	v_pk_add_f32 v[62:63], v[236:237], v[62:63]
	v_pk_add_f32 v[64:65], v[234:235], v[64:65]
	v_pk_add_f32 v[66:67], v[238:239], v[66:67]
	v_pk_add_f32 v[62:63], v[244:245], v[62:63]
	v_pk_add_f32 v[60:61], v[240:241], v[60:61]
	v_pk_add_f32 v[66:67], v[246:247], v[66:67]
	v_pk_add_f32 v[64:65], v[242:243], v[64:65]
	v_cvt_pk_bf16_f32 v216, v216, v217
	v_cvt_pk_bf16_f32 v217, v218, v219
	v_cvt_pk_bf16_f32 v218, v224, v225
	v_cvt_pk_bf16_f32 v219, v228, v229
	v_cvt_pk_bf16_f32 v220, v220, v221
	v_cvt_pk_bf16_f32 v221, v222, v223
	v_cvt_pk_bf16_f32 v222, v226, v227
	v_cvt_pk_bf16_f32 v223, v230, v231
	v_cvt_pk_bf16_f32 v224, v232, v233
	v_cvt_pk_bf16_f32 v225, v236, v237
	v_cvt_pk_bf16_f32 v226, v240, v241
	v_cvt_pk_bf16_f32 v227, v244, v245
	v_cvt_pk_bf16_f32 v228, v234, v235
	v_cvt_pk_bf16_f32 v229, v238, v239
	v_cvt_pk_bf16_f32 v230, v242, v243
	v_cvt_pk_bf16_f32 v231, v246, v247
	ds_read_b64_tr_b16 v[232:233], v208 offset:53248
	ds_read_b64_tr_b16 v[236:237], v208 offset:53280
	ds_read_b64_tr_b16 v[234:235], v208 offset:57856
	ds_read_b64_tr_b16 v[240:241], v208 offset:62464
	ds_read_b64_tr_b16 v[242:243], v209 offset:4608
	ds_read_b64_tr_b16 v[238:239], v208 offset:57888
	ds_read_b64_tr_b16 v[244:245], v208 offset:62496
	ds_read_b64_tr_b16 v[246:247], v210 offset:4608
	v_exp_f32_e64 v85, -v84
	v_mov_b32_e32 v68, v64
	v_mov_b32_e32 v69, v60
	v_mov_b32_e32 v60, v65
	v_mov_b32_e32 v64, v66
	v_mov_b32_e32 v65, v62
	v_mov_b32_e32 v62, v67
	v_pk_add_f32 v[60:61], v[68:69], v[60:61]
	v_pk_add_f32 v[62:63], v[64:65], v[62:63]
	v_mul_f32_e32 v100, v150, v85
	v_pk_add_f32 v[60:61], v[60:61], v[62:63]
	v_add_f32_e32 v214, v215, v84
	v_sub_f32_e32 v47, v79, v84
	v_sub_f32_e32 v46, v78, v84
	v_sub_f32_e32 v45, v77, v84
	v_sub_f32_e32 v44, v76, v84
	v_sub_f32_e32 v51, v99, v84
	v_sub_f32_e32 v50, v98, v84
	v_sub_f32_e32 v49, v97, v84
	v_sub_f32_e32 v48, v96, v84
	v_sub_f32_e32 v55, v107, v84
	v_sub_f32_e32 v54, v106, v84
	v_sub_f32_e32 v53, v105, v84
	v_sub_f32_e32 v52, v104, v84
	v_sub_f32_e32 v59, v83, v84
	v_sub_f32_e32 v58, v82, v84
	v_sub_f32_e32 v57, v81, v84
	v_sub_f32_e32 v56, v80, v84
	v_pk_fma_f32 v[156:157], v[158:159], v[100:101], v[60:61] op_sel_hi:[1,0,1]
	v_pk_mul_f32 v[62:63], v[122:123], v[100:101] op_sel_hi:[1,0]
	v_pk_mul_f32 v[60:61], v[120:121], v[100:101] op_sel_hi:[1,0]
	v_pk_mul_f32 v[66:67], v[118:119], v[100:101] op_sel_hi:[1,0]
	v_pk_mul_f32 v[64:65], v[116:117], v[100:101] op_sel_hi:[1,0]
	v_pk_mul_f32 v[70:71], v[114:115], v[100:101] op_sel_hi:[1,0]
	v_pk_mul_f32 v[68:69], v[112:113], v[100:101] op_sel_hi:[1,0]
	v_pk_mul_f32 v[74:75], v[110:111], v[100:101] op_sel_hi:[1,0]
	v_pk_mul_f32 v[72:73], v[108:109], v[100:101] op_sel_hi:[1,0]
	v_pk_mul_f32 v[86:87], v[138:139], v[100:101] op_sel_hi:[1,0]
	v_pk_mul_f32 v[84:85], v[136:137], v[100:101] op_sel_hi:[1,0]
	v_pk_mul_f32 v[90:91], v[134:135], v[100:101] op_sel_hi:[1,0]
	v_pk_mul_f32 v[88:89], v[132:133], v[100:101] op_sel_hi:[1,0]
	v_pk_mul_f32 v[94:95], v[130:131], v[100:101] op_sel_hi:[1,0]
	v_pk_mul_f32 v[92:93], v[128:129], v[100:101] op_sel_hi:[1,0]
	v_pk_mul_f32 v[102:103], v[126:127], v[100:101] op_sel_hi:[1,0]
	v_pk_mul_f32 v[100:101], v[124:125], v[100:101] op_sel_hi:[1,0]
	s_setprio 1
	s_waitcnt lgkmcnt(5)
; #define LAS __attribute__((address_space(3)))
; #define MFMA16(a, b, c) __builtin_amdgcn_mfma_f32_16x16x32_bf16((a), (b), (c), 0, 0, 0)
; DI u32x2 tr4(const LAS unsigned char* p) { return __builtin_bit_cast(u32x2, __builtin_amdgcn_ds_read_tr16_b64_v4i16((LAS v4i16_t*)p)); }
; DI bf16x8 packp(f32x4 a, f32x4 b) { return __builtin_bit_cast(bf16x8, pack8(a, b)); }
; DI void atb_commit(const AtRawB& r, LAS unsigned char* buf, int tid) {
; #pragma unroll
;     for (int c = 0; c < 2; ++c) { const int e = tid + c * NTHR, key = e >> 4, c8 = (e & 15) * 8;
;         *(LAS u32x4*)(buf + AT_K + key * 272 + c8 * 2) = r.k[c]; *(LAS u32x4*)(buf + AT_V + key * 288 + c8 * 2) = r.v[c]; }
; }
; DI void at_pv(AtState& S, const f32x4 (&s1)[4], const f32x4 (&s2)[4], float alpha, float ps1, float ps2, const LAS unsigned char* buf, int hh, int fq, int tq, int tp) {
;     S.l1 = S.l1 * alpha + ps1; S.l2 = S.l2 * alpha + ps2;
; #pragma unroll
;     for (int dt = 0; dt < 4; ++dt) { S.O1[dt] = S.O1[dt] * alpha; S.O2[dt] = S.O2[dt] * alpha; }
;     bf16x8 p1[2], p2[2];
; #pragma unroll
;     for (int s = 0; s < 2; ++s) { p1[s] = packp(s1[2 * s], s1[2 * s + 1]); p2[s] = packp(s2[2 * s], s2[2 * s + 1]); }
; #pragma unroll
;     for (int dh = 0; dh < 2; ++dh) {
;         bf16x8 vt[2][2];
; #pragma unroll
;         for (int d2 = 0; d2 < 2; ++d2)
; #pragma unroll
;             for (int s = 0; s < 2; ++s) { const int dt = 2 * dh + d2; const LAS unsigned char* vr = buf + AT_V + (32 * s + 4 * fq + tq) * 288 + (hh * 64 + 16 * dt + 4 * tp) * 2; vt[d2][s] = cat44(tr4(vr), tr4(vr + 16 * 288)); }
;         __builtin_amdgcn_s_setprio(1);
; #pragma unroll
;         for (int s = 0; s < 2; ++s)
; #pragma unroll
;             for (int d2 = 0; d2 < 2; ++d2) { const int dt = 2 * dh + d2; S.O1[dt] = MFMA16(vt[d2][s], p1[s], S.O1[dt]); S.O2[dt] = MFMA16(vt[d2][s], p2[s], S.O2[dt]); }
;         __builtin_amdgcn_s_setprio(0);
;         __builtin_amdgcn_sched_barrier(0);
;     }
	v_mfma_f32_16x16x32_bf16 v[60:63], v[232:235], v[216:219], v[60:63]
	v_mfma_f32_16x16x32_bf16 v[232:235], v[232:235], v[220:223], v[64:67]
	s_waitcnt lgkmcnt(2)
	v_mfma_f32_16x16x32_bf16 v[68:71], v[236:239], v[216:219], v[68:71]
	v_mfma_f32_16x16x32_bf16 v[236:239], v[236:239], v[220:223], v[72:75]
	v_mfma_f32_16x16x32_bf16 v[64:67], v[240:243], v[224:227], v[60:63]
	v_mfma_f32_16x16x32_bf16 v[72:75], v[240:243], v[228:231], v[232:235]
	s_waitcnt lgkmcnt(0)
	v_mfma_f32_16x16x32_bf16 v[60:63], v[244:247], v[224:227], v[68:71]
	v_mfma_f32_16x16x32_bf16 v[68:71], v[244:247], v[228:231], v[236:239]
	s_setprio 0
	ds_read_b64_tr_b16 v[232:233], v208 offset:53312
	s_nop 0
	ds_read_b64_tr_b16 v[236:237], v208 offset:53344
	ds_read_b64_tr_b16 v[234:235], v208 offset:57920
	ds_read_b64_tr_b16 v[238:239], v208 offset:57952
	ds_read_b64_tr_b16 v[240:241], v208 offset:62528
	ds_read_b64_tr_b16 v[242:243], v211 offset:4608
	ds_read_b64_tr_b16 v[246:247], v212 offset:4608
	ds_read_b64_tr_b16 v[244:245], v208 offset:62560
	s_setprio 1
	s_waitcnt lgkmcnt(5)
	v_mfma_f32_16x16x32_bf16 v[84:87], v[232:235], v[216:219], v[84:87]
	v_mfma_f32_16x16x32_bf16 v[232:235], v[232:235], v[220:223], v[88:91]
	s_waitcnt lgkmcnt(4)
	v_mfma_f32_16x16x32_bf16 v[92:95], v[236:239], v[216:219], v[92:95]
	v_mfma_f32_16x16x32_bf16 v[216:219], v[236:239], v[220:223], v[100:103]
	s_waitcnt lgkmcnt(2)
	v_mfma_f32_16x16x32_bf16 v[88:91], v[240:243], v[224:227], v[84:87]
	v_mfma_f32_16x16x32_bf16 v[100:103], v[240:243], v[228:231], v[232:235]
	s_waitcnt lgkmcnt(0)
	v_mfma_f32_16x16x32_bf16 v[84:87], v[244:247], v[224:227], v[92:95]
	v_mfma_f32_16x16x32_bf16 v[92:95], v[244:247], v[228:231], v[216:219]
	s_setprio 0
	s_cbranch_execnz .LBB0_1390
.LBB0_1389:
	s_nop 0
	v_cvt_pk_bf16_f32 v216, v164, v165
	v_cvt_pk_bf16_f32 v219, v176, v177
	v_cvt_pk_bf16_f32 v165, v174, v175
	ds_read_b64_tr_b16 v[60:61], v208 offset:53248
	ds_read_b64_tr_b16 v[64:65], v208 offset:53280
	ds_read_b64_tr_b16 v[62:63], v208 offset:57856
	ds_read_b64_tr_b16 v[68:69], v208 offset:62464
	ds_read_b64_tr_b16 v[70:71], v209 offset:4608
	ds_read_b64_tr_b16 v[66:67], v208 offset:57888
	ds_read_b64_tr_b16 v[174:175], v208 offset:62496
	ds_read_b64_tr_b16 v[176:177], v210 offset:4608
	v_mov_b32_e32 v151, v150
	v_pk_fma_f32 v[156:157], v[154:155], v[158:159], v[194:195]
	v_pk_mul_f32 v[46:47], v[150:151], v[122:123]
	v_pk_mul_f32 v[44:45], v[152:153], v[120:121]
	v_pk_mul_f32 v[50:51], v[150:151], v[118:119]
	v_pk_mul_f32 v[48:49], v[152:153], v[116:117]
	v_pk_mul_f32 v[54:55], v[150:151], v[114:115]
	v_pk_mul_f32 v[52:53], v[152:153], v[112:113]
	v_pk_mul_f32 v[58:59], v[150:151], v[110:111]
	v_pk_mul_f32 v[56:57], v[152:153], v[108:109]
	v_pk_mul_f32 v[86:87], v[150:151], v[138:139]
	v_pk_mul_f32 v[84:85], v[152:153], v[136:137]
	v_pk_mul_f32 v[90:91], v[150:151], v[134:135]
	v_pk_mul_f32 v[88:89], v[152:153], v[132:133]
	v_pk_mul_f32 v[94:95], v[150:151], v[130:131]
	v_pk_mul_f32 v[92:93], v[152:153], v[128:129]
	v_pk_mul_f32 v[102:103], v[150:151], v[126:127]
	v_pk_mul_f32 v[100:101], v[152:153], v[124:125]
	v_cvt_pk_bf16_f32 v217, v168, v169
	v_cvt_pk_bf16_f32 v218, v172, v173
	v_cvt_pk_bf16_f32 v162, v162, v163
	v_cvt_pk_bf16_f32 v163, v166, v167
	v_cvt_pk_bf16_f32 v164, v170, v171
	v_cvt_pk_bf16_f32 v166, v180, v181
	v_cvt_pk_bf16_f32 v167, v184, v185
	v_cvt_pk_bf16_f32 v168, v188, v189
	v_cvt_pk_bf16_f32 v169, v192, v193
	v_cvt_pk_bf16_f32 v170, v178, v179
	v_cvt_pk_bf16_f32 v171, v182, v183
	v_cvt_pk_bf16_f32 v172, v186, v187
	v_cvt_pk_bf16_f32 v173, v190, v191
	s_setprio 1
	s_waitcnt lgkmcnt(5)
	v_mfma_f32_16x16x32_bf16 v[44:47], v[60:63], v[216:219], v[44:47]
	v_mfma_f32_16x16x32_bf16 v[48:51], v[60:63], v[162:165], v[48:51]
	s_waitcnt lgkmcnt(2)
	v_mfma_f32_16x16x32_bf16 v[52:55], v[64:67], v[216:219], v[52:55]
	v_mfma_f32_16x16x32_bf16 v[56:59], v[64:67], v[162:165], v[56:59]
	v_mfma_f32_16x16x32_bf16 v[64:67], v[68:71], v[166:169], v[44:47]
	v_mfma_f32_16x16x32_bf16 v[72:75], v[68:71], v[170:173], v[48:51]
	s_waitcnt lgkmcnt(0)
	v_mfma_f32_16x16x32_bf16 v[60:63], v[174:177], v[166:169], v[52:55]
	v_mfma_f32_16x16x32_bf16 v[68:71], v[174:177], v[170:173], v[56:59]
	s_setprio 0
	s_waitcnt vmcnt(4)
	ds_write_b128 v143, v[28:31]
	ds_write_b128 v202, v[32:35] offset:17408
	ds_write_b128 v203, v[36:39]
	ds_write_b128 v204, v[40:43] offset:17408
	ds_read_b64_tr_b16 v[44:45], v208 offset:53312
	ds_read_b64_tr_b16 v[48:49], v208 offset:53344
	ds_read_b64_tr_b16 v[46:47], v208 offset:57920
	ds_read_b64_tr_b16 v[50:51], v208 offset:57952
	ds_read_b64_tr_b16 v[52:53], v208 offset:62528
	ds_read_b64_tr_b16 v[54:55], v211 offset:4608
	ds_read_b64_tr_b16 v[58:59], v212 offset:4608
	ds_read_b64_tr_b16 v[56:57], v208 offset:62560
	s_setprio 1
	s_waitcnt lgkmcnt(5)
	v_mfma_f32_16x16x32_bf16 v[84:87], v[44:47], v[216:219], v[84:87]
	v_mfma_f32_16x16x32_bf16 v[44:47], v[44:47], v[162:165], v[88:91]
	s_waitcnt lgkmcnt(4)
	v_mfma_f32_16x16x32_bf16 v[92:95], v[48:51], v[216:219], v[92:95]
	v_mfma_f32_16x16x32_bf16 v[48:51], v[48:51], v[162:165], v[100:103]
	s_waitcnt lgkmcnt(2)
	v_mfma_f32_16x16x32_bf16 v[88:91], v[52:55], v[166:169], v[84:87]
	v_mfma_f32_16x16x32_bf16 v[100:103], v[52:55], v[170:173], v[44:47]
	s_waitcnt lgkmcnt(0)
	v_mfma_f32_16x16x32_bf16 v[84:87], v[56:59], v[166:169], v[92:95]
	v_mfma_f32_16x16x32_bf16 v[92:95], v[56:59], v[170:173], v[48:51]
	s_setprio 0
	v_mov_b64_e32 v[56:57], v[80:81]
	v_mov_b64_e32 v[44:45], v[76:77]
	v_mov_b64_e32 v[48:49], v[96:97]
	v_mov_b64_e32 v[52:53], v[104:105]
	v_mov_b32_e32 v214, v215
	v_mov_b64_e32 v[58:59], v[82:83]
	v_mov_b64_e32 v[46:47], v[78:79]
	v_mov_b64_e32 v[50:51], v[98:99]
	v_mov_b64_e32 v[54:55], v[106:107]
	s_mov_b64 s[14:15], 0
	s_branch .Lcommit_done_B

; DI void lds_barrier() { asm volatile("s_waitcnt lgkmcnt(0)" ::: "memory"); __builtin_amdgcn_s_barrier(); asm volatile("" ::: "memory"); }
; template <int VAR>
; DI void attn_segment(const Args& a, const Frame& F, int l, int qrow0, int qpos0, int hp, int ntile, int nf32, const float* ck, const float* cv, int prow0) {
;     ...
;             atb_commit(rb, F.lds + (kt & 1) * AT_BUF, tid);
;             lds_barrier();
;         }
.Lcommit_done_B:
	s_waitcnt lgkmcnt(0)
	s_barrier
	s_addk_i32 s23, 0xff80
	s_add_i32 s26, s26, 2
	s_cmp_ge_i32 s27, s24
	s_cselect_b64 s[14:15], -1, 0
	s_and_b64 vcc, exec, s[14:15]
	s_cbranch_vccz .LBB0_1376
	s_branch .LBB0_1397
